# C2 rows dealt as balanced contiguous per-wave ranges (6 rows per wave on the 32 workgroups with a fifth C1 tile, 9/8 elsewhere) instead of the strided deal
# speedup vs baseline: 1.0095x; 1.0095x over previous
; __global__ void __launch_bounds__(NWAVES * 64, 2) mk_fwd(Args args) {
;     ...
;                 for (int m = gw; m < M; m += ngw) {
;                     const bool smp = m >= MP;
;                     const int b = smp ? ((m - MP) >> 5) : (m >> 12), t = smp ? ((m - MP) & 31) : (m & 4095);
;                     const int pos = smp ? PAST + t : t;
;                     const int T = smp ? DS : SEQ;
;                     const size_t lrow = smp ? (size_t)MP + (size_t)b * SKEYS + PAST + t : (size_t)m;
;                     float* lat_out = smp ? out + O_LATS + ((size_t)(l * DB + b) * DS + t) * KVL : out + O_LATP + ((size_t)(l * NB + b) * SEQ + t) * KVL;
;                     float* kr_out = smp ? out + O_KRS + ((size_t)(l * DB + b) * DS + t) * ROPE : out + O_KRP + ((size_t)(l * NB + b) * SEQ + t) * ROPE;
;                     const bf16_t* prow = proj + (size_t)m * NPAD;
.LBB0_498:
	v_readlane_b32 s36, v252, 4
	s_lshl_b64 s[2:3], s[48:49], 2
	v_readlane_b32 s42, v252, 10
	v_readlane_b32 s37, v252, 5
	v_readlane_b32 s43, v252, 11
	s_add_u32 s36, s42, s2
	v_readlane_b32 s38, v252, 6
	s_addc_u32 s37, s43, s3
	s_ashr_i32 s2, s10, 6
	s_lshl_b32 s3, s1, 3
	s_add_i32 s38, s3, s2
	s_cmp_lt_u32 s38, 0x100
	s_cbranch_scc0 .Lc2r_b
	s_mul_i32 s98, s38, 6
	s_add_i32 s99, s98, 5
	s_branch .Lc2r_done
.Lc2r_b:
	s_sub_i32 s99, s38, 0x100
	s_cmp_lt_u32 s99, 0x400
	s_cbranch_scc0 .Lc2r_c
	s_mul_i32 s98, s99, 9
	s_add_i32 s98, s98, 0x600
	s_add_i32 s99, s98, 8
	s_branch .Lc2r_done
.Lc2r_c:
	s_sub_i32 s99, s99, 0x400
	s_lshl_b32 s98, s99, 3
	s_add_i32 s98, s98, 0x2a00
	s_add_i32 s99, s98, 7
.Lc2r_done:
	s_mov_b32 s38, s98
	s_mov_b32 s98, s99
	s_mov_b32 s50, 1
	s_add_u32 s2, s52, 0x4a700000
	s_addc_u32 s3, s53, 0
	v_writelane_b32 v254, s2, 62
	v_and_b32_e32 v108, 63, v109
	v_readlane_b32 s39, v252, 7
	v_writelane_b32 v254, s3, 63
	s_add_u32 s2, s52, 0x4d800000
	s_addc_u32 s3, s53, 0
	v_writelane_b32 v255, s2, 0
	s_cmpk_gt_i32 s38, 0x41ff
	v_readlane_b32 s40, v252, 8
	v_writelane_b32 v255, s3, 1
	v_readlane_b32 s41, v252, 9
	s_waitcnt vmcnt(0) lgkmcnt(0)
	s_barrier
	s_cbranch_scc1 .LBB0_597
	s_add_u32 s52, s52, 0x100000
	v_readlane_b32 s56, v252, 4
	s_addc_u32 s53, s53, 0
	s_lshl_b64 s[2:3], s[54:55], 2
	v_readlane_b32 s58, v252, 6
	v_readlane_b32 s59, v252, 7
	s_add_u32 s4, s58, s2
	v_readlane_b32 s40, v254, 54
	s_addc_u32 s5, s59, s3
	s_mul_i32 s6, s40, 0x3000
	v_readlane_b32 s57, v252, 5
	v_readlane_b32 s60, v252, 8
	v_readlane_b32 s61, v252, 9
	v_readlane_b32 s62, v252, 10
	v_readlane_b32 s63, v252, 11
	s_add_u32 s6, s56, s6
	v_readlane_b32 s41, v254, 55
	s_addc_u32 s7, s57, 0
	v_readlane_b32 s56, v252, 18
	s_lshl_b64 s[8:9], s[40:41], 8
	v_readlane_b32 s70, v252, 32
	v_readlane_b32 s71, v252, 33
	s_add_u32 s8, s70, s8
	s_addc_u32 s9, s71, s9
	s_lshl_b64 s[54:55], s[40:41], 11
	v_readlane_b32 s57, v252, 19
	v_readlane_b32 s58, v252, 20
	v_readlane_b32 s59, v252, 21
	v_readlane_b32 s60, v252, 22
	v_readlane_b32 s61, v252, 23
	v_readlane_b32 s62, v252, 24
	v_readlane_b32 s63, v252, 25
	v_readlane_b32 s64, v252, 26
	v_readlane_b32 s65, v252, 27
	v_readlane_b32 s66, v252, 28
	v_readlane_b32 s67, v252, 29
	v_readlane_b32 s68, v252, 30
	v_readlane_b32 s69, v252, 31
	s_add_u32 s54, s56, s54
	s_addc_u32 s55, s57, s55
	v_readlane_b32 s56, v252, 52
	v_readlane_b32 s70, v253, 2
	v_readlane_b32 s71, v253, 3
	s_add_u32 s2, s70, s2
	s_addc_u32 s3, s71, s3
	s_add_u32 s19, s36, 0x10800000
	s_addc_u32 s72, s37, 0
	s_lshl_b32 s73, s40, 2
	s_add_u32 s74, s36, 0x15229000
	s_addc_u32 s75, s37, 0
	s_lshl_b32 s76, s40, 4
	s_add_u32 s77, s36, 0x14800000
	s_addc_u32 s78, s37, 0
	s_add_u32 s79, s36, 0x15429000
	v_cmp_lt_i32_e32 vcc, v192, v191
	s_addc_u32 s96, s37, 0
	s_add_u32 s97, s36, 0x15219000
	v_cndmask_b32_e32 v8, v190, v192, vcc
	v_cmp_lt_i32_e32 vcc, v193, v191
	v_xor_b32_e32 v2, 4, v190
	s_addc_u32 s40, s37, 0
	v_cndmask_b32_e32 v9, v190, v193, vcc
	v_cmp_lt_i32_e32 vcc, v202, v191
	s_add_u32 s41, s36, 0x15ccd000
	s_addc_u32 s42, s37, 0
	v_cndmask_b32_e32 v10, v190, v202, vcc
	v_cmp_lt_i32_e32 vcc, v2, v191
	s_ashr_i32 s39, s38, 31
	s_ashr_i32 s51, s50, 31
	v_cndmask_b32_e32 v11, v190, v2, vcc
	v_lshlrev_b32_e32 v2, 5, v108
	v_lshl_add_u64 v[110:111], s[2:3], 0, v[2:3]
	v_lshl_add_u64 v[118:119], s[6:7], 0, v[2:3]
	s_lshl_b64 s[2:3], s[38:39], 11
	v_readlane_b32 s6, v252, 12
	v_readlane_b32 s7, v252, 13
	s_add_u32 s2, s6, s2
	v_lshl_add_u64 v[112:113], s[54:55], 0, v[2:3]
	v_lshlrev_b32_e32 v4, 4, v108
	v_mov_b32_e32 v5, v3
	v_lshl_add_u64 v[116:117], s[4:5], 0, v[2:3]
	s_addc_u32 s3, s7, s3
	s_lshl_b64 s[54:55], s[50:51], 11
	s_mul_i32 s5, s38, 0x5e00
	v_lshl_add_u64 v[120:121], s[2:3], 0, v[4:5]
	s_mul_hi_i32 s4, s38, 0x5e00
	s_add_u32 s2, s6, s5
	s_addc_u32 s3, s7, s4
	v_lshl_add_u64 v[122:123], s[2:3], 0, v[4:5]
	s_lshl_b64 s[2:3], s[38:39], 13
	s_add_u32 s2, s6, s2
	v_readlane_b32 s57, v252, 53
	s_addc_u32 s3, s7, s3
	v_lshl_add_u64 v[124:125], s[2:3], 0, v[4:5]
	s_lshl_b64 s[56:57], s[50:51], 13
	v_readlane_b32 s2, v254, 31
	s_add_u32 s2, s2, s5
	v_readlane_b32 s3, v254, 32
	s_addc_u32 s3, s3, s4
	v_readlane_b32 s4, v254, 62
	v_readlane_b32 s5, v254, 63
	v_cmp_lt_i32_e32 vcc, v196, v191
	v_readlane_b32 s58, v252, 54
	v_lshl_add_u64 v[128:129], s[4:5], 0, v[4:5]
	v_readlane_b32 s4, v255, 0
	v_lshlrev_b32_e32 v4, 1, v108
	v_readlane_b32 s5, v255, 1
	v_cndmask_b32_e32 v12, v190, v196, vcc
	v_cmp_lt_i32_e32 vcc, v197, v191
	v_lshl_add_u64 v[130:131], s[4:5], 0, v[4:5]
	s_mov_b64 s[4:5], 0x1000
	v_lshl_add_u64 v[132:133], v[118:119], 0, s[4:5]
	s_mov_b64 s[4:5], 0x2000
	v_lshl_add_u64 v[134:135], v[118:119], 0, s[4:5]
	s_mov_b64 s[4:5], 0x800
	v_lshl_add_u64 v[136:137], v[118:119], 0, s[4:5]
	s_mov_b64 s[4:5], 0x1800
	v_readlane_b32 s59, v252, 55
	v_readlane_b32 s60, v252, 56
	v_readlane_b32 s61, v252, 57
	v_cndmask_b32_e32 v13, v190, v197, vcc
	v_lshlrev_b32_e32 v6, 2, v108
	v_mov_b32_e32 v7, v3
	v_lshl_add_u64 v[138:139], v[118:119], 0, s[4:5]
	s_mov_b64 s[4:5], 0x2800
	v_lshl_add_u64 v[114:115], s[8:9], 0, v[6:7]
	v_lshlrev_b32_e32 v126, 3, v108
	v_lshlrev_b32_e32 v174, 2, v8
	v_lshlrev_b32_e32 v175, 2, v9
	v_lshlrev_b32_e32 v176, 2, v10
	v_lshlrev_b32_e32 v177, 2, v11
	v_lshlrev_b32_e32 v178, 2, v12
	v_lshlrev_b32_e32 v179, 2, v13
	v_lshl_add_u64 v[140:141], v[118:119], 0, s[4:5]
	v_lshl_add_u64 v[142:143], s[2:3], 0, v[4:5]
	s_mul_hi_i32 s59, s50, 0x5e00
	s_mul_i32 s58, s50, 0x5e00
	v_lshlrev_b32_e32 v180, 2, v108
	v_cmp_gt_u32_e64 s[2:3], 32, v108
	s_mov_b64 s[60:61], s[38:39]
	v_readlane_b32 s62, v252, 58
	v_readlane_b32 s63, v252, 59
; __device__ __forceinline__ float siluf_(float x) { return x * __builtin_amdgcn_rcpf(1.0f + __expf(-x)); }
; __device__ __forceinline__ u32x4 pack8(const float* f) { u32x4 w; w.x = cvtpk(f[0], f[1]); w.y = cvtpk(f[2], f[3]); w.z = cvtpk(f[4], f[5]); w.w = cvtpk(f[6], f[7]); return w; }
; __device__ __forceinline__ bf16x8 pack8(const f32x4& a, const f32x4& b) { u32x4 w; w.x = cpk(a.x, a.y); w.y = cpk(a.z, a.w); w.z = cpk(b.x, b.y); w.w = cpk(b.z, b.w); return __builtin_bit_cast(bf16x8, w); }
; __global__ void __launch_bounds__(NWAVES * 64, 2) mk_fwd(Args args) {
;     ...
;                 for (int m = gw; m < M; m += ngw) {
;                     const bool smp = m >= MP;
;                     const int b = smp ? ((m - MP) >> 5) : (m >> 12), t = smp ? ((m - MP) & 31) : (m & 4095);
;                     const int pos = smp ? PAST + t : t;
;                     const int T = smp ? DS : SEQ;
;                     const size_t lrow = smp ? (size_t)MP + (size_t)b * SKEYS + PAST + t : (size_t)m;
;                     float* lat_out = smp ? out + O_LATS + ((size_t)(l * DB + b) * DS + t) * KVL : out + O_LATP + ((size_t)(l * NB + b) * SEQ + t) * KVL;
;                     float* kr_out = smp ? out + O_KRS + ((size_t)(l * DB + b) * DS + t) * ROPE : out + O_KRP + ((size_t)(l * NB + b) * SEQ + t) * ROPE;
;                     const bf16_t* prow = proj + (size_t)m * NPAD;
;                     const u32x4 rq0 = *(const u32x4*)(prow + C_CQ + lane * 8), rq1 = *(const u32x4*)(prow + C_CQ + 512 + lane * 8), rkv = *(const u32x4*)(prow + C_CKV + lane * 8);
;     ...
;                     for (int j = 0; j < 6; ++j) {
;                         const int c = j * 512 + lane * 8;
;                         float f[8]; unpack8(rgt[j], f);
; #pragma unroll
;                         for (int e = 0; e < 8; ++e) f[e] = siluf_(f[e]);
;                         *(u32x4*)(hmix + (size_t)m * DM + c) = pack8(f);
;                     }
	v_readlane_b32 s64, v252, 60
	v_readlane_b32 s65, v252, 61
	v_readlane_b32 s66, v252, 62
	v_readlane_b32 s67, v252, 63
	v_readlane_b32 s68, v253, 0
	v_readlane_b32 s69, v253, 1
	global_load_dwordx4 v[206:209], v[110:111], off offset:2048
	global_load_dwordx4 v[210:213], v[110:111], off offset:2064
	global_load_dwordx4 v[214:217], v[112:113], off
	global_load_dwordx4 v[218:221], v[112:113], off offset:16
	global_load_dwordx4 v[222:225], v[116:117], off offset:16
	global_load_dwordx4 v[226:229], v[116:117], off
	global_load_dwordx4 v[230:233], v[118:119], off offset:16
	global_load_dwordx4 v[234:237], v[118:119], off
	global_load_dwordx4 v[240:243], v[132:133], off offset:16
	global_load_dwordx4 v[244:247], v[132:133], off
	global_load_dwordx4 v[184:187], v[134:135], off offset:16
	global_load_dwordx2 v[194:195], v[134:135], off
	global_load_dwordx2 v[248:249], v[134:135], off offset:8
	global_load_dword v238, v[114:115], off
	global_load_dwordx4 v[40:43], v[116:117], off offset:2064
	global_load_dwordx4 v[60:63], v[116:117], off offset:2048
	global_load_dwordx4 v[48:51], v[136:137], off offset:16
	global_load_dwordx4 v[72:75], v[136:137], off
	global_load_dwordx4 v[52:55], v[138:139], off offset:16
	global_load_dwordx4 v[64:67], v[138:139], off
	global_load_dwordx4 v[56:59], v[140:141], off offset:16
	global_load_dwordx4 v[68:71], v[140:141], off
	v_lshrrev_b32_e32 v181, 6, v0
	v_and_b32_e32 v4, 63, v0
	v_lshlrev_b32_e32 v181, 13, v181
	v_lshl_add_u32 v181, v4, 4, v181
	s_waitcnt vmcnt(0)
	ds_write_b128 v181, v[40:43]
	ds_write_b128 v181, v[60:63] offset:1024
	ds_write_b128 v181, v[48:51] offset:2048
	ds_write_b128 v181, v[72:75] offset:3072
	ds_write_b128 v181, v[52:55] offset:4096
	ds_write_b128 v181, v[64:67] offset:5120
	ds_write_b128 v181, v[56:59] offset:6144
	ds_write_b128 v181, v[68:71] offset:7168
	s_waitcnt lgkmcnt(0)
	s_branch .LBB0_501
.LBB0_500:
	v_lshlrev_b32_e32 v2, 16, v24
	v_mul_f32_e32 v31, 0xbfb8aa3b, v2
	v_exp_f32_e32 v31, v31
	v_and_b32_e32 v24, 0xffff0000, v24
	v_lshlrev_b32_e32 v28, 16, v25
	v_and_b32_e32 v25, 0xffff0000, v25
	v_add_f32_e32 v31, 1.0, v31
	v_rcp_f32_e32 v31, v31
	v_lshlrev_b32_e32 v29, 16, v26
	v_and_b32_e32 v26, 0xffff0000, v26
	v_lshlrev_b32_e32 v30, 16, v27
	v_mul_f32_e32 v2, v31, v2
	v_mul_f32_e32 v31, 0xbfb8aa3b, v24
	v_exp_f32_e32 v31, v31
	v_and_b32_e32 v27, 0xffff0000, v27
	s_mov_b32 s4, 0xaf00000
	s_add_u32 s60, s60, s50
	v_add_f32_e32 v31, 1.0, v31
	v_rcp_f32_e32 v31, v31
	s_addc_u32 s61, s61, s51
	v_lshl_add_u64 v[120:121], v[120:121], 0, s[54:55]
	v_lshl_add_u64 v[122:123], v[122:123], 0, s[58:59]
	v_mul_f32_e32 v24, v31, v24
	v_mul_f32_e32 v31, 0xbfb8aa3b, v28
	v_exp_f32_e32 v31, v31
	v_lshl_add_u64 v[124:125], v[124:125], 0, s[56:57]
	v_lshl_add_u64 v[142:143], v[142:143], 0, s[58:59]
	s_cmp_gt_i32 s60, s98
	v_add_f32_e32 v31, 1.0, v31
	v_rcp_f32_e32 v31, v31
	s_nop 0
	v_mul_f32_e32 v31, v31, v28
	v_mul_f32_e32 v28, 0xbfb8aa3b, v25
	v_exp_f32_e32 v28, v28
	s_nop 0
	v_add_f32_e32 v28, 1.0, v28
	v_rcp_f32_e32 v28, v28
	s_nop 0
	v_mul_f32_e32 v25, v28, v25
	v_mul_f32_e32 v28, 0xbfb8aa3b, v29
	v_exp_f32_e32 v28, v28
	s_nop 0
	v_add_f32_e32 v28, 1.0, v28
	v_rcp_f32_e32 v28, v28
	s_nop 0
	v_mul_f32_e32 v32, v28, v29
	v_mul_f32_e32 v28, 0xbfb8aa3b, v26
	v_exp_f32_e32 v28, v28
	s_nop 0
	v_add_f32_e32 v28, 1.0, v28
	v_rcp_f32_e32 v28, v28
	s_nop 0
	v_mul_f32_e32 v26, v28, v26
	v_mul_f32_e32 v28, 0xbfb8aa3b, v30
	v_exp_f32_e32 v28, v28
	s_nop 0
	v_add_f32_e32 v28, 1.0, v28
	v_rcp_f32_e32 v28, v28
	s_nop 0
	v_mul_f32_e32 v33, v28, v30
	v_mul_f32_e32 v28, 0xbfb8aa3b, v27
	v_exp_f32_e32 v28, v28
	s_nop 0
	v_add_f32_e32 v28, 1.0, v28
	v_rcp_f32_e32 v28, v28
	s_nop 0
	v_mul_f32_e32 v27, v28, v27
	v_cvt_pk_bf16_f32 v28, v2, v24
	v_cvt_pk_bf16_f32 v29, v31, v25
	v_cvt_pk_bf16_f32 v30, v32, v26
	v_add_co_u32_e32 v26, vcc, s4, v80
	v_cvt_pk_bf16_f32 v31, v33, v27
	s_mov_b32 s4, 0xaf01000
	s_nop 0
	v_addc_co_u32_e32 v27, vcc, 0, v81, vcc
	v_add_co_u32_e32 v24, vcc, s4, v80
	v_lshlrev_b32_e32 v2, 16, v20
	s_nop 0
	v_addc_co_u32_e32 v25, vcc, 0, v81, vcc
	global_store_dwordx4 v[24:25], v[28:31], off offset:-4096
	v_and_b32_e32 v20, 0xffff0000, v20
	s_nop 0
	v_mul_f32_e32 v31, 0xbfb8aa3b, v2
	v_exp_f32_e32 v31, v31
	v_lshlrev_b32_e32 v28, 16, v21
	v_and_b32_e32 v21, 0xffff0000, v21
	v_lshlrev_b32_e32 v29, 16, v22
	v_add_f32_e32 v31, 1.0, v31
	v_rcp_f32_e32 v31, v31
	v_and_b32_e32 v22, 0xffff0000, v22
	v_lshlrev_b32_e32 v30, 16, v23
	v_and_b32_e32 v23, 0xffff0000, v23
	v_mul_f32_e32 v2, v31, v2
	v_mul_f32_e32 v31, 0xbfb8aa3b, v20
	v_exp_f32_e32 v31, v31
	s_nop 0
	v_add_f32_e32 v31, 1.0, v31
	v_rcp_f32_e32 v31, v31
	s_nop 0
	v_mul_f32_e32 v20, v31, v20
	v_mul_f32_e32 v31, 0xbfb8aa3b, v28
	v_exp_f32_e32 v31, v31
	v_cvt_pk_bf16_f32 v20, v2, v20
	v_lshlrev_b32_e32 v2, 16, v16
	v_and_b32_e32 v16, 0xffff0000, v16
	v_add_f32_e32 v31, 1.0, v31
	v_rcp_f32_e32 v31, v31
	s_nop 0
	v_mul_f32_e32 v28, v31, v28
	v_mul_f32_e32 v31, 0xbfb8aa3b, v21
	v_exp_f32_e32 v31, v31
	s_nop 0
	v_add_f32_e32 v31, 1.0, v31
	v_rcp_f32_e32 v31, v31
	s_nop 0
	v_mul_f32_e32 v21, v31, v21
	v_mul_f32_e32 v31, 0xbfb8aa3b, v29
	v_exp_f32_e32 v31, v31
	v_cvt_pk_bf16_f32 v21, v28, v21
	s_nop 0
	v_add_f32_e32 v31, 1.0, v31
	v_rcp_f32_e32 v31, v31
	s_nop 0
	v_mul_f32_e32 v29, v31, v29
	v_mul_f32_e32 v31, 0xbfb8aa3b, v22
	v_exp_f32_e32 v31, v31
	s_nop 0
	v_add_f32_e32 v31, 1.0, v31
	v_rcp_f32_e32 v31, v31
	s_nop 0
	v_mul_f32_e32 v22, v31, v22
	v_mul_f32_e32 v31, 0xbfb8aa3b, v30
	v_exp_f32_e32 v31, v31
	v_cvt_pk_bf16_f32 v22, v29, v22
	s_nop 0
	v_add_f32_e32 v31, 1.0, v31
	v_rcp_f32_e32 v31, v31
	s_nop 0
	v_mul_f32_e32 v30, v31, v30
; __device__ __forceinline__ float siluf_(float x) { return x * __builtin_amdgcn_rcpf(1.0f + __expf(-x)); }
; __device__ __forceinline__ u32x4 pack8(const float* f) { u32x4 w; w.x = cvtpk(f[0], f[1]); w.y = cvtpk(f[2], f[3]); w.z = cvtpk(f[4], f[5]); w.w = cvtpk(f[6], f[7]); return w; }
; __device__ __forceinline__ bf16x8 pack8(const f32x4& a, const f32x4& b) { u32x4 w; w.x = cpk(a.x, a.y); w.y = cpk(a.z, a.w); w.z = cpk(b.x, b.y); w.w = cpk(b.z, b.w); return __builtin_bit_cast(bf16x8, w); }
; __global__ void __launch_bounds__(NWAVES * 64, 2) mk_fwd(Args args) {
;     ...
;                     for (int j = 0; j < 6; ++j) {
;                         const int c = j * 512 + lane * 8;
;                         float f[8]; unpack8(rgt[j], f);
; #pragma unroll
;                         for (int e = 0; e < 8; ++e) f[e] = siluf_(f[e]);
;                         *(u32x4*)(hmix + (size_t)m * DM + c) = pack8(f);
;                     }
	v_mul_f32_e32 v31, 0xbfb8aa3b, v23
	v_exp_f32_e32 v31, v31
	s_nop 0
	v_add_f32_e32 v31, 1.0, v31
	v_rcp_f32_e32 v31, v31
	s_nop 0
	v_mul_f32_e32 v23, v31, v23
	v_cvt_pk_bf16_f32 v23, v30, v23
	global_store_dwordx4 v[26:27], v[20:23], off offset:1024
	s_nop 1
	v_mul_f32_e32 v23, 0xbfb8aa3b, v2
	v_exp_f32_e32 v23, v23
	v_lshlrev_b32_e32 v20, 16, v17
	v_and_b32_e32 v17, 0xffff0000, v17
	v_lshlrev_b32_e32 v21, 16, v18
	v_add_f32_e32 v23, 1.0, v23
	v_rcp_f32_e32 v23, v23
	v_and_b32_e32 v18, 0xffff0000, v18
	v_lshlrev_b32_e32 v22, 16, v19
	v_and_b32_e32 v19, 0xffff0000, v19
	v_mul_f32_e32 v2, v23, v2
	v_mul_f32_e32 v23, 0xbfb8aa3b, v16
	v_exp_f32_e32 v23, v23
	s_nop 0
	v_add_f32_e32 v23, 1.0, v23
	v_rcp_f32_e32 v23, v23
	s_nop 0
	v_mul_f32_e32 v16, v23, v16
	v_mul_f32_e32 v23, 0xbfb8aa3b, v20
	v_exp_f32_e32 v23, v23
	v_cvt_pk_bf16_f32 v16, v2, v16
	v_lshlrev_b32_e32 v2, 16, v12
	v_and_b32_e32 v12, 0xffff0000, v12
	v_add_f32_e32 v23, 1.0, v23
	v_rcp_f32_e32 v23, v23
	s_nop 0
	v_mul_f32_e32 v20, v23, v20
	v_mul_f32_e32 v23, 0xbfb8aa3b, v17
	v_exp_f32_e32 v23, v23
	s_nop 0
	v_add_f32_e32 v23, 1.0, v23
	v_rcp_f32_e32 v23, v23
	s_nop 0
	v_mul_f32_e32 v17, v23, v17
	v_mul_f32_e32 v23, 0xbfb8aa3b, v21
	v_exp_f32_e32 v23, v23
	v_cvt_pk_bf16_f32 v17, v20, v17
	s_nop 0
	v_add_f32_e32 v23, 1.0, v23
	v_rcp_f32_e32 v23, v23
	s_nop 0
	v_mul_f32_e32 v21, v23, v21
	v_mul_f32_e32 v23, 0xbfb8aa3b, v18
	v_exp_f32_e32 v23, v23
	s_nop 0
	v_add_f32_e32 v23, 1.0, v23
	v_rcp_f32_e32 v23, v23
	s_nop 0
	v_mul_f32_e32 v18, v23, v18
	v_mul_f32_e32 v23, 0xbfb8aa3b, v22
	v_exp_f32_e32 v23, v23
	v_cvt_pk_bf16_f32 v18, v21, v18
	s_nop 0
	v_add_f32_e32 v23, 1.0, v23
	v_rcp_f32_e32 v23, v23
	s_nop 0
	v_mul_f32_e32 v22, v23, v22
	v_mul_f32_e32 v23, 0xbfb8aa3b, v19
	v_exp_f32_e32 v23, v23
	s_nop 0
	v_add_f32_e32 v23, 1.0, v23
	v_rcp_f32_e32 v23, v23
	s_nop 0
	v_mul_f32_e32 v19, v23, v19
	v_cvt_pk_bf16_f32 v19, v22, v19
	global_store_dwordx4 v[26:27], v[16:19], off offset:2048
	s_nop 1
	v_mul_f32_e32 v19, 0xbfb8aa3b, v2
	v_exp_f32_e32 v19, v19
	v_lshlrev_b32_e32 v16, 16, v13
	v_and_b32_e32 v13, 0xffff0000, v13
	v_lshlrev_b32_e32 v17, 16, v14
	v_add_f32_e32 v19, 1.0, v19
	v_rcp_f32_e32 v19, v19
	v_and_b32_e32 v14, 0xffff0000, v14
	v_lshlrev_b32_e32 v18, 16, v15
	v_and_b32_e32 v15, 0xffff0000, v15
	v_mul_f32_e32 v2, v19, v2
	v_mul_f32_e32 v19, 0xbfb8aa3b, v12
	v_exp_f32_e32 v19, v19
	s_nop 0
	v_add_f32_e32 v19, 1.0, v19
	v_rcp_f32_e32 v19, v19
	s_nop 0
	v_mul_f32_e32 v12, v19, v12
	v_mul_f32_e32 v19, 0xbfb8aa3b, v16
	v_exp_f32_e32 v19, v19
	v_cvt_pk_bf16_f32 v12, v2, v12
	v_lshlrev_b32_e32 v2, 16, v8
	v_and_b32_e32 v8, 0xffff0000, v8
	v_add_f32_e32 v19, 1.0, v19
	v_rcp_f32_e32 v19, v19
	s_nop 0
	v_mul_f32_e32 v16, v19, v16
	v_mul_f32_e32 v19, 0xbfb8aa3b, v13
	v_exp_f32_e32 v19, v19
	s_nop 0
	v_add_f32_e32 v19, 1.0, v19
	v_rcp_f32_e32 v19, v19
	s_nop 0
	v_mul_f32_e32 v13, v19, v13
	v_mul_f32_e32 v19, 0xbfb8aa3b, v17
	v_exp_f32_e32 v19, v19
	v_cvt_pk_bf16_f32 v13, v16, v13
	s_nop 0
	v_add_f32_e32 v19, 1.0, v19
	v_rcp_f32_e32 v19, v19
	s_nop 0
	v_mul_f32_e32 v17, v19, v17
	v_mul_f32_e32 v19, 0xbfb8aa3b, v14
	v_exp_f32_e32 v19, v19
	s_nop 0
	v_add_f32_e32 v19, 1.0, v19
	v_rcp_f32_e32 v19, v19
	s_nop 0
	v_mul_f32_e32 v14, v19, v14
	v_mul_f32_e32 v19, 0xbfb8aa3b, v18
	v_exp_f32_e32 v19, v19
	v_cvt_pk_bf16_f32 v14, v17, v14
	s_nop 0
	v_add_f32_e32 v19, 1.0, v19
	v_rcp_f32_e32 v19, v19
	s_nop 0
	v_mul_f32_e32 v18, v19, v18
	v_mul_f32_e32 v19, 0xbfb8aa3b, v15
	v_exp_f32_e32 v19, v19
	s_nop 0
	v_add_f32_e32 v19, 1.0, v19
	v_rcp_f32_e32 v19, v19
	s_nop 0
	v_mul_f32_e32 v15, v19, v15
	v_cvt_pk_bf16_f32 v15, v18, v15
	global_store_dwordx4 v[26:27], v[12:15], off offset:3072
	s_nop 1
	v_mul_f32_e32 v15, 0xbfb8aa3b, v2
	v_exp_f32_e32 v15, v15
	v_lshlrev_b32_e32 v12, 16, v9
	v_and_b32_e32 v9, 0xffff0000, v9
	v_lshlrev_b32_e32 v13, 16, v10
	v_add_f32_e32 v15, 1.0, v15
	v_rcp_f32_e32 v15, v15
	v_and_b32_e32 v10, 0xffff0000, v10
	v_lshlrev_b32_e32 v14, 16, v11
	v_and_b32_e32 v11, 0xffff0000, v11
	v_mul_f32_e32 v2, v15, v2
	v_mul_f32_e32 v15, 0xbfb8aa3b, v8
	v_exp_f32_e32 v15, v15
	s_nop 0
	v_add_f32_e32 v15, 1.0, v15
	v_rcp_f32_e32 v15, v15
	s_nop 0
	v_mul_f32_e32 v8, v15, v8
	v_mul_f32_e32 v15, 0xbfb8aa3b, v12
	v_exp_f32_e32 v15, v15
	v_cvt_pk_bf16_f32 v8, v2, v8
	v_lshlrev_b32_e32 v2, 16, v4
	v_and_b32_e32 v4, 0xffff0000, v4
	v_add_f32_e32 v15, 1.0, v15
	v_rcp_f32_e32 v15, v15
	s_nop 0
	v_mul_f32_e32 v12, v15, v12
	v_mul_f32_e32 v15, 0xbfb8aa3b, v9
	v_exp_f32_e32 v15, v15
	s_nop 0
	v_add_f32_e32 v15, 1.0, v15
	v_rcp_f32_e32 v15, v15
	s_nop 0
	v_mul_f32_e32 v9, v15, v9
	v_mul_f32_e32 v15, 0xbfb8aa3b, v13
	v_exp_f32_e32 v15, v15
	v_cvt_pk_bf16_f32 v9, v12, v9
	s_nop 0
	v_add_f32_e32 v15, 1.0, v15
	v_rcp_f32_e32 v15, v15
	s_nop 0
	v_mul_f32_e32 v13, v15, v13
	v_mul_f32_e32 v15, 0xbfb8aa3b, v10
	v_exp_f32_e32 v15, v15
	s_nop 0
	v_add_f32_e32 v15, 1.0, v15
	v_rcp_f32_e32 v15, v15
	s_nop 0
	v_mul_f32_e32 v10, v15, v10
	v_mul_f32_e32 v15, 0xbfb8aa3b, v14
	v_exp_f32_e32 v15, v15
	v_cvt_pk_bf16_f32 v10, v13, v10
	s_nop 0
	v_add_f32_e32 v15, 1.0, v15
	v_rcp_f32_e32 v15, v15
	s_nop 0
	v_mul_f32_e32 v14, v15, v14
	v_mul_f32_e32 v15, 0xbfb8aa3b, v11
	v_exp_f32_e32 v15, v15
	s_nop 0
	v_add_f32_e32 v15, 1.0, v15
	v_rcp_f32_e32 v15, v15
	s_nop 0
	v_mul_f32_e32 v11, v15, v11
	v_cvt_pk_bf16_f32 v11, v14, v11
	global_store_dwordx4 v[24:25], v[8:11], off
	s_nop 1
	v_mul_f32_e32 v11, 0xbfb8aa3b, v2
	v_exp_f32_e32 v11, v11
	v_lshlrev_b32_e32 v8, 16, v5
	v_and_b32_e32 v5, 0xffff0000, v5
	v_lshlrev_b32_e32 v9, 16, v6
	v_add_f32_e32 v11, 1.0, v11
	v_rcp_f32_e32 v11, v11
	v_and_b32_e32 v6, 0xffff0000, v6
	v_lshlrev_b32_e32 v10, 16, v7
	v_and_b32_e32 v7, 0xffff0000, v7
	v_mul_f32_e32 v2, v11, v2
	v_mul_f32_e32 v11, 0xbfb8aa3b, v4
	v_exp_f32_e32 v11, v11
	s_nop 0
	v_add_f32_e32 v11, 1.0, v11
	v_rcp_f32_e32 v11, v11
	s_nop 0
	v_mul_f32_e32 v4, v11, v4
	v_mul_f32_e32 v11, 0xbfb8aa3b, v8
	v_exp_f32_e32 v11, v11
	v_cvt_pk_bf16_f32 v4, v2, v4
	s_nop 0
	v_add_f32_e32 v11, 1.0, v11
	v_rcp_f32_e32 v11, v11
	s_nop 0
	v_mul_f32_e32 v8, v11, v8
	v_mul_f32_e32 v11, 0xbfb8aa3b, v5
	v_exp_f32_e32 v11, v11
	s_nop 0
	v_add_f32_e32 v11, 1.0, v11
	v_rcp_f32_e32 v11, v11
	s_nop 0
	v_mul_f32_e32 v5, v11, v5
	v_mul_f32_e32 v11, 0xbfb8aa3b, v9
	v_exp_f32_e32 v11, v11
	v_cvt_pk_bf16_f32 v5, v8, v5
	s_nop 0
	v_add_f32_e32 v11, 1.0, v11
	v_rcp_f32_e32 v11, v11
	s_nop 0
	v_mul_f32_e32 v9, v11, v9
	v_mul_f32_e32 v11, 0xbfb8aa3b, v6
	v_exp_f32_e32 v11, v11
	s_nop 0
	v_add_f32_e32 v11, 1.0, v11
	v_rcp_f32_e32 v11, v11
	s_nop 0
	v_mul_f32_e32 v6, v11, v6
	v_mul_f32_e32 v11, 0xbfb8aa3b, v10
	v_exp_f32_e32 v11, v11
	v_cvt_pk_bf16_f32 v6, v9, v6
	s_nop 0
	v_add_f32_e32 v11, 1.0, v11
	v_rcp_f32_e32 v11, v11
	s_nop 0
	v_mul_f32_e32 v10, v11, v10
	v_mul_f32_e32 v11, 0xbfb8aa3b, v7
	v_exp_f32_e32 v11, v11
	s_nop 0
	v_add_f32_e32 v11, 1.0, v11
	v_rcp_f32_e32 v11, v11
	s_nop 0
	v_mul_f32_e32 v7, v11, v7
	v_cvt_pk_bf16_f32 v7, v10, v7
	global_store_dwordx4 v[24:25], v[4:7], off offset:1024
	s_cbranch_scc1 .LBB0_597

; __device__ __forceinline__ unsigned cvtpk(float lo, float hi) { unsigned r; asm volatile("v_cvt_pk_bf16_f32 %0, %1, %2" : "=v"(r) : "v"(lo), "v"(hi)); return r; }
; __device__ __forceinline__ bf16_t f2bf(float f) { return (bf16_t)(cvtpk(f, 0.f) & 0xffffu); }
; __global__ void __launch_bounds__(NWAVES * 64, 2) mk_fwd(Args args) {
;     ...
;             {
;                 const float* clat = args.in[4] + (size_t)l * DB * PAST * KVL; const float* ckr = args.in[5] + (size_t)l * DB * PAST * ROPE;
;                 if (G == 256) {
;                     for (int r0 = gw; r0 < DB * PAST; r0 += 8 * 2048) {
;                         f32x4 a0[8], a1[8]; float kx[8];
; #pragma unroll
;                         for (int q = 0; q < 8; ++q) { const int r = r0 + q * 2048;
;                             a0[q] = *(const f32x4*)(clat + (size_t)r * KVL + lane * 8); a1[q] = *(const f32x4*)(clat + (size_t)r * KVL + lane * 8 + 4); kx[q] = ckr[(size_t)r * ROPE + lane]; }
; #pragma unroll
;                         for (int q = 0; q < 8; ++q) { const int r = r0 + q * 2048;
;                             const int b = r >> 11, p = r & 2047; const size_t lrow = (size_t)MP + (size_t)b * SKEYS + p;
;                             u32x4 w; w.x = cvtpk(a0[q].x, a0[q].y); w.y = cvtpk(a0[q].z, a0[q].w); w.z = cvtpk(a1[q].x, a1[q].y); w.w = cvtpk(a1[q].z, a1[q].w);
;                             *(u32x4*)(latall + lrow * KVL + lane * 8) = w;
;                             Krb[lrow * ROPE + lane] = f2bf(kx[q]); }
.LBB0_597:
	v_readfirstlane_b32 s38, v0
	s_lshl_b32 s50, s0, 3
	s_and_b32 s38, s38, 0x3ff
	s_lshr_b32 s38, s38, 6
	s_lshl_b32 s99, s1, 3
	s_add_i32 s38, s38, s99
	v_readlane_b32 s2, v254, 54
	v_readlane_b32 s3, v254, 55
	s_lshl_b64 s[64:65], s[2:3], 26
	s_lshl_b64 s[66:67], s[2:3], 23
	s_cmp_lt_i32 s38, 0x8000
	s_cselect_b64 s[2:3], -1, 0
	v_cndmask_b32_e64 v2, 0, 1, s[2:3]
	s_cmpk_eq_i32 s0, 0x100
	s_mov_b64 s[4:5], -1
	v_cmp_ne_u32_e64 s[2:3], 1, v2
	s_cbranch_scc1 .LBB0_602
	s_and_b64 vcc, exec, s[2:3]
	s_cbranch_vccnz .LBB0_601
	v_readlane_b32 s4, v254, 62
	v_lshlrev_b32_e32 v2, 4, v108
	v_readlane_b32 s5, v254, 63
	s_ashr_i32 s39, s38, 31
	v_readlane_b32 s68, v252, 36
	v_lshl_add_u64 v[4:5], s[4:5], 0, v[2:3]
	v_readlane_b32 s4, v255, 0
	v_lshlrev_b32_e32 v2, 1, v108
	v_readlane_b32 s5, v255, 1
	v_readlane_b32 s69, v252, 37
	v_readlane_b32 s70, v252, 38
	v_lshl_add_u64 v[6:7], s[4:5], 0, v[2:3]
	s_lshl_b64 s[4:5], s[38:39], 8
	v_readlane_b32 s71, v252, 39
	v_readlane_b32 s72, v252, 40
	v_readlane_b32 s73, v252, 41
	v_readlane_b32 s74, v252, 42
	v_readlane_b32 s75, v252, 43
	v_readlane_b32 s76, v252, 44
	v_readlane_b32 s77, v252, 45
	s_add_u32 s4, s66, s4
	v_readlane_b32 s78, v252, 46
	v_readlane_b32 s79, v252, 47
	v_readlane_b32 s80, v252, 48
	v_readlane_b32 s81, v252, 49
	v_readlane_b32 s82, v252, 50
	v_readlane_b32 s83, v252, 51
	s_mov_b64 s[68:69], s[76:77]
	s_addc_u32 s5, s67, s5
	s_mov_b64 s[70:71], s[78:79]
	s_add_u32 s4, s70, s4
	v_lshlrev_b32_e32 v2, 2, v108
	s_addc_u32 s5, s71, s5
	s_ashr_i32 s51, s50, 31
	v_lshl_add_u64 v[8:9], s[4:5], 0, v[2:3]
	s_lshl_b64 s[4:5], s[50:51], 8
	s_lshl_b64 s[6:7], s[38:39], 11
	s_add_u32 s6, s64, s6
	s_addc_u32 s7, s65, s7
	v_readlane_b32 s8, v254, 33
	s_add_u32 s6, s8, s6
	v_readlane_b32 s8, v254, 34
	v_lshlrev_b32_e32 v2, 5, v108
	s_addc_u32 s7, s8, s7
	v_lshl_add_u64 v[10:11], s[6:7], 0, v[2:3]
	s_lshl_b64 s[6:7], s[50:51], 11
	s_mov_b32 s10, s38
	s_mov_b64 s[72:73], s[80:81]
	s_mov_b64 s[74:75], s[82:83]
